# attention next-tile K/V staging moved into S-phase MFMA shadow; rstd sum-of-squares loops software pipelined
# speedup vs baseline: 1.0859x; 1.0004x over previous
; DI int otid() { int t = (int)__builtin_amdgcn_workitem_id_x(); asm volatile("" : "+v"(t)); return t; }
; DI float ld_f(const bf16* p) { return bf2f(*p); }
; template <typename AT>
; DI void compute_rstd2(const AT* A, int lda, int Kn, float* rstd, int rows) {
;   const int tid = otid();
;   const int tpr = NTHR / rows;
;   const int row = tid / tpr, part = tid % tpr;
;   const AT* p = A + (size_t)row * lda + part * (Kn / tpr);
;   float s = 0.f;
;   for (int k = 0; k < Kn / tpr; ++k) { const float v = ld_f(p + k); s += v * v; }
;   s += __shfl_xor(s, 1); if (tpr == 4) s += __shfl_xor(s, 2);
;   __syncthreads();
;   if (part == 0) rstd[row] = rsqrtf(s / (float)Kn + EPS);
;   __syncthreads();
; }
.LBB0_232:
	s_and_b32 s15, s14, 0x7f
	s_cmp_lg_u32 s15, s6
	s_mov_b64 s[4:5], -1
	s_cbranch_scc0 .LBB0_238
	v_mov_b32_e32 v0, v186
	s_and_b32 s4, s13, 0x7f
	v_lshrrev_b32_e32 v2, 31, v0
	v_add_u32_e32 v3, v0, v2
	v_ashrrev_i32_e32 v2, 1, v3
	v_and_b32_e32 v3, -2, v3
	v_sub_u32_e32 v0, v0, v3
	v_ashrrev_i32_e32 v3, 31, v2
	s_lshl_b32 s82, s4, 20
	v_lshlrev_b64 v[4:5], 12, v[2:3]
	v_lshlrev_b32_e32 v6, 9, v0
	v_ashrrev_i32_e32 v7, 31, v6
	v_lshl_add_u64 v[4:5], s[82:83], 0, v[4:5]
	v_readlane_b32 s4, v226, 19
	v_lshl_add_u64 v[4:5], v[6:7], 2, v[4:5]
	v_readlane_b32 s5, v226, 20
	v_mov_b32_e32 v3, 0
	s_nop 0
	v_lshl_add_u64 v[4:5], s[4:5], 0, v[4:5]
	s_mov_b64 s[4:5], 0
	v_mov_b32_e32 v246, v4
	v_mov_b32_e32 v247, v5
	s_mov_b32 s4, 0
	global_load_dwordx4 v[6:9], v[246:247], off
	global_load_dwordx4 v[10:13], v[246:247], off offset:16
	global_load_dwordx4 v[14:17], v[246:247], off offset:32
	global_load_dwordx4 v[18:21], v[246:247], off offset:48
	v_lshl_add_u64 v[246:247], v[246:247], 0, 64
.Lrstd_inproj_loop:
	global_load_dwordx4 v[230:233], v[246:247], off
	global_load_dwordx4 v[234:237], v[246:247], off offset:16
	global_load_dwordx4 v[238:241], v[246:247], off offset:32
	global_load_dwordx4 v[242:245], v[246:247], off offset:48
	v_lshl_add_u64 v[246:247], v[246:247], 0, 64
	s_waitcnt vmcnt(4)
	v_fmac_f32_e32 v3, v6, v6
	v_fmac_f32_e32 v3, v7, v7
	v_fmac_f32_e32 v3, v8, v8
	v_fmac_f32_e32 v3, v9, v9
	v_fmac_f32_e32 v3, v10, v10
	v_fmac_f32_e32 v3, v11, v11
	v_fmac_f32_e32 v3, v12, v12
	v_fmac_f32_e32 v3, v13, v13
	v_fmac_f32_e32 v3, v14, v14
	v_fmac_f32_e32 v3, v15, v15
	v_fmac_f32_e32 v3, v16, v16
	v_fmac_f32_e32 v3, v17, v17
	v_fmac_f32_e32 v3, v18, v18
	v_fmac_f32_e32 v3, v19, v19
	v_fmac_f32_e32 v3, v20, v20
	v_fmac_f32_e32 v3, v21, v21
	s_add_u32 s4, s4, 128
	s_cmpk_eq_i32 s4, 0x800
	s_cbranch_scc1 .Lrstd_inproj_last
	global_load_dwordx4 v[6:9], v[246:247], off
	global_load_dwordx4 v[10:13], v[246:247], off offset:16
	global_load_dwordx4 v[14:17], v[246:247], off offset:32
	global_load_dwordx4 v[18:21], v[246:247], off offset:48
	v_lshl_add_u64 v[246:247], v[246:247], 0, 64
	s_waitcnt vmcnt(4)
	v_fmac_f32_e32 v3, v230, v230
	v_fmac_f32_e32 v3, v231, v231
	v_fmac_f32_e32 v3, v232, v232
	v_fmac_f32_e32 v3, v233, v233
	v_fmac_f32_e32 v3, v234, v234
	v_fmac_f32_e32 v3, v235, v235
	v_fmac_f32_e32 v3, v236, v236
	v_fmac_f32_e32 v3, v237, v237
	v_fmac_f32_e32 v3, v238, v238
	v_fmac_f32_e32 v3, v239, v239
	v_fmac_f32_e32 v3, v240, v240
	v_fmac_f32_e32 v3, v241, v241
	v_fmac_f32_e32 v3, v242, v242
	v_fmac_f32_e32 v3, v243, v243
	v_fmac_f32_e32 v3, v244, v244
	v_fmac_f32_e32 v3, v245, v245
	s_branch .Lrstd_inproj_loop
.Lrstd_inproj_last:
	s_waitcnt vmcnt(0)
	v_fmac_f32_e32 v3, v230, v230
	v_fmac_f32_e32 v3, v231, v231
	v_fmac_f32_e32 v3, v232, v232
	v_fmac_f32_e32 v3, v233, v233
	v_fmac_f32_e32 v3, v234, v234
	v_fmac_f32_e32 v3, v235, v235
	v_fmac_f32_e32 v3, v236, v236
	v_fmac_f32_e32 v3, v237, v237
	v_fmac_f32_e32 v3, v238, v238
	v_fmac_f32_e32 v3, v239, v239
	v_fmac_f32_e32 v3, v240, v240
	v_fmac_f32_e32 v3, v241, v241
	v_fmac_f32_e32 v3, v242, v242
	v_fmac_f32_e32 v3, v243, v243
	v_fmac_f32_e32 v3, v244, v244
	v_fmac_f32_e32 v3, v245, v245
	v_and_b32_e32 v5, 64, v189
	v_xor_b32_e32 v4, 1, v189
	v_add_u32_e32 v5, 64, v5
	v_cmp_lt_i32_e32 vcc, v4, v5
	s_barrier
	s_nop 0
	v_cndmask_b32_e32 v4, v189, v4, vcc
	v_lshlrev_b32_e32 v4, 2, v4
	ds_bpermute_b32 v4, v4, v3
	v_cmp_eq_u32_e32 vcc, 0, v0
	s_waitcnt lgkmcnt(0)
	s_and_saveexec_b64 s[4:5], vcc
	s_cbranch_execz .LBB0_237
	v_add_f32_e32 v0, v3, v4
	v_fmamk_f32 v0, v0, 0x3a800000, v187
	s_mov_b32 s7, 0x800000
	v_mul_f32_e32 v3, 0x4b800000, v0
	v_cmp_gt_f32_e32 vcc, s7, v0
	v_lshl_add_u32 v2, v2, 2, v190
	v_add_u32_e32 v2, 0x24000, v2
	v_cndmask_b32_e32 v0, v0, v3, vcc
	v_rsq_f32_e32 v0, v0
	s_nop 0
	v_mul_f32_e32 v3, 0x45800000, v0
	v_cndmask_b32_e32 v0, v0, v3, vcc
	ds_write_b32 v2, v0

; #define MFMA32(a, b, c) __builtin_amdgcn_mfma_f32_32x32x16_bf16((a), (b), (c), 0, 0, 0)
; #define ATT_LOAD(KT)                                                                                    \
;   { _Pragma("unroll") for (int r = 0; r < 3; ++r) rk[r] = *(const u32x4*)(Kg + (size_t)((KT) * 64 + krow[r]) * 768 + kseg[r]); \
;     _Pragma("unroll") for (int r = 0; r < 2; ++r) rv[r] = *(const u32x4*)(Vg + (size_t)(vrow0 + 64 * r) * L + (KT) * 64 + vseg); }
; DI void attn_item(const Ctx& c, int item) {
;     ...
; #pragma unroll
;     for (int ks = 0; ks < 12; ++ks)
; #pragma unroll
;       for (int kg = 0; kg < 2; ++kg) {
;         const bf16x8 a = *(const bf16x8*)(ks_ + (kg * 32 + r32) * 200 + ks * 16 + 8 * hh);
;         s[kg] = MFMA32(a, bq[ks], s[kg]);
;       }
;     float mx = s[0][0];
; #pragma unroll
;     for (int kg = 0; kg < 2; ++kg)
; #pragma unroll
;       for (int i = 0; i < 16; ++i) mx = fmaxf(mx, s[kg][i]);
;     mx = fmaxf(mx, __shfl_xor(mx, 32));
;     const float mn = fmaxf(m_, mx * sc);
;     const float alpha = __builtin_amdgcn_exp2f(m_ - mn);
;     m_ = mn;
;     float ps = 0.f;
; #pragma unroll
;     for (int kg = 0; kg < 2; ++kg)
; #pragma unroll
;       for (int i = 0; i < 16; ++i) { s[kg][i] = __builtin_amdgcn_exp2f(s[kg][i] * sc - mn); ps += s[kg][i]; }
;     l_ = l_ * alpha + ps;
;     if (__builtin_amdgcn_ballot_w64(alpha != 1.0f) != 0ull) {
;     ...
;     if (kt + 1 < ntile) ATT_STORE((kt + 1) & 1)
;     if (kt + 2 < ntile) ATT_LOAD(kt + 2)
.LBB0_547:
	s_and_b32 s0, s4, 1
	s_mul_i32 s1, s0, 0x6400
	v_mov_b32_e32 v0, v211
	v_add_u32_e32 v211, s1, v208
	ds_read_b128 v[230:233], v211
	ds_read_b128 v[234:237], v211 offset:12800
	ds_read_b128 v[238:241], v211 offset:32
	ds_read_b128 v[242:245], v211 offset:12832
	s_waitcnt lgkmcnt(3)
	v_mfma_f32_32x32x16_bf16 v[82:97], v[230:233], v[98:101], 0
	ds_read_b128 v[230:233], v211 offset:64
	s_waitcnt lgkmcnt(3)
	v_mfma_f32_32x32x16_bf16 v[66:81], v[234:237], v[98:101], 0
	ds_read_b128 v[234:237], v211 offset:12864
	s_waitcnt lgkmcnt(3)
	v_mfma_f32_32x32x16_bf16 v[82:97], v[238:241], v[102:105], v[82:97]
	ds_read_b128 v[238:241], v211 offset:96
	s_waitcnt lgkmcnt(3)
	v_mfma_f32_32x32x16_bf16 v[66:81], v[242:245], v[102:105], v[66:81]
	ds_read_b128 v[242:245], v211 offset:12896
	s_waitcnt lgkmcnt(3)
	v_mfma_f32_32x32x16_bf16 v[82:97], v[230:233], v[106:109], v[82:97]
	ds_read_b128 v[230:233], v211 offset:128
	s_waitcnt lgkmcnt(3)
	v_mfma_f32_32x32x16_bf16 v[66:81], v[234:237], v[106:109], v[66:81]
	ds_read_b128 v[234:237], v211 offset:12928
	s_waitcnt lgkmcnt(3)
	v_mfma_f32_32x32x16_bf16 v[82:97], v[238:241], v[110:113], v[82:97]
	ds_read_b128 v[238:241], v211 offset:160
	s_waitcnt lgkmcnt(3)
	v_mfma_f32_32x32x16_bf16 v[66:81], v[242:245], v[110:113], v[66:81]
	ds_read_b128 v[242:245], v211 offset:12960
	s_add_i32 s100, s4, 1
	s_cmp_ge_u32 s100, s8
	s_cbranch_scc1 .Lattn_nostore
	s_bitcmp1_b32 s100, 0
	s_cselect_b32 s101, 0x6400, 0
	s_cselect_b32 vcc_hi, 0x4800, 0
	s_addk_i32 s101, 0x50
	v_lshlrev_b32_e32 v212, 1, v168
	v_add3_u32 v212, s101, v169, v212
	s_waitcnt vmcnt(4)
	ds_write_b128 v212, v[146:149]
	v_lshlrev_b32_e32 v212, 1, v170
	v_add3_u32 v212, s101, v171, v212
	s_waitcnt vmcnt(3)
	ds_write_b128 v212, v[150:153]
	v_lshlrev_b32_e32 v212, 1, v172
	v_add3_u32 v212, s101, v173, v212
	s_waitcnt vmcnt(2)
	ds_write_b128 v212, v[154:157]
	v_add_u32_e32 v212, vcc_hi, v206
	v_add_u32_e32 v213, 0xc800, v212
	v_add_u32_e32 v212, 0xe800, v212
	s_waitcnt vmcnt(1)
	ds_write2_b64 v213, v[158:159], v[160:161] offset1:2
	s_waitcnt vmcnt(0)
	ds_write2_b64 v212, v[162:163], v[164:165] offset0:128 offset1:130
.Lattn_nostore:
	s_add_i32 s101, s4, 2
	s_cmp_ge_u32 s101, s8
	s_cbranch_scc1 .Lattn_noload
	s_waitcnt vmcnt(4)
	v_add_u32_e32 v146, s82, v203
	v_add_u32_e32 v148, s82, v204
	s_waitcnt vmcnt(2)
	v_add_u32_e32 v154, s82, v205
	s_waitcnt vmcnt(0)
	v_lshl_add_u64 v[162:163], s[82:83], 1, v[174:175]
	v_mad_i64_i32 v[146:147], vcc, v146, s10, v[180:181]
	v_mad_i64_i32 v[150:151], vcc, v148, s10, v[182:183]
	v_mad_i64_i32 v[154:155], vcc, v154, s10, v[184:185]
	v_lshl_add_u64 v[158:159], v[176:177], 1, v[162:163]
	v_lshl_add_u64 v[162:163], v[178:179], 1, v[162:163]
	global_load_dwordx4 v[146:149], v[146:147], off
	s_nop 0
	global_load_dwordx4 v[150:153], v[150:151], off
	s_nop 0
	global_load_dwordx4 v[154:157], v[154:155], off
	s_nop 0
	global_load_dwordx4 v[158:161], v[158:159], off
	s_nop 0
	global_load_dwordx4 v[162:165], v[162:163], off
.Lattn_noload:
	s_waitcnt lgkmcnt(3)
	v_mfma_f32_32x32x16_bf16 v[82:97], v[230:233], v[114:117], v[82:97]
	ds_read_b128 v[230:233], v211 offset:192
	s_waitcnt lgkmcnt(3)
	v_mfma_f32_32x32x16_bf16 v[66:81], v[234:237], v[114:117], v[66:81]
	ds_read_b128 v[234:237], v211 offset:12992
	s_waitcnt lgkmcnt(3)
	v_mfma_f32_32x32x16_bf16 v[82:97], v[238:241], v[118:121], v[82:97]
	ds_read_b128 v[238:241], v211 offset:224
	s_waitcnt lgkmcnt(3)
	v_mfma_f32_32x32x16_bf16 v[66:81], v[242:245], v[118:121], v[66:81]
	ds_read_b128 v[242:245], v211 offset:13024
	s_waitcnt lgkmcnt(3)
	v_mfma_f32_32x32x16_bf16 v[82:97], v[230:233], v[122:125], v[82:97]
	ds_read_b128 v[230:233], v211 offset:256
	s_waitcnt lgkmcnt(3)
	v_mfma_f32_32x32x16_bf16 v[66:81], v[234:237], v[122:125], v[66:81]
	ds_read_b128 v[234:237], v211 offset:13056
	s_waitcnt lgkmcnt(3)
	v_mfma_f32_32x32x16_bf16 v[82:97], v[238:241], v[126:129], v[82:97]
	ds_read_b128 v[238:241], v211 offset:288
	s_waitcnt lgkmcnt(3)
	v_mfma_f32_32x32x16_bf16 v[66:81], v[242:245], v[126:129], v[66:81]
	ds_read_b128 v[242:245], v211 offset:13088
	s_waitcnt lgkmcnt(3)
	v_mfma_f32_32x32x16_bf16 v[82:97], v[230:233], v[130:133], v[82:97]
	ds_read_b128 v[230:233], v211 offset:320
	s_waitcnt lgkmcnt(3)
	v_mfma_f32_32x32x16_bf16 v[66:81], v[234:237], v[130:133], v[66:81]
	ds_read_b128 v[234:237], v211 offset:13120
	s_waitcnt lgkmcnt(3)
	v_mfma_f32_32x32x16_bf16 v[82:97], v[238:241], v[134:137], v[82:97]
	ds_read_b128 v[238:241], v211 offset:352
	s_waitcnt lgkmcnt(3)
	v_mfma_f32_32x32x16_bf16 v[66:81], v[242:245], v[134:137], v[66:81]
	ds_read_b128 v[242:245], v211 offset:13152
	s_waitcnt lgkmcnt(3)
	v_mfma_f32_32x32x16_bf16 v[82:97], v[230:233], v[138:141], v[82:97]
	s_waitcnt lgkmcnt(2)
	v_mfma_f32_32x32x16_bf16 v[66:81], v[234:237], v[138:141], v[66:81]
	s_waitcnt lgkmcnt(1)
	v_mfma_f32_32x32x16_bf16 v[82:97], v[238:241], v[142:145], v[82:97]
	s_waitcnt lgkmcnt(0)
	v_mfma_f32_32x32x16_bf16 v[66:81], v[242:245], v[142:145], v[66:81]
	s_mulk_i32 s0, 0x4800
	v_add_u32_e32 v224, s0, v209
	ds_read_b128 v[230:233], v224 offset:51200
	ds_read_b128 v[234:237], v224 offset:55808
	ds_read_b128 v[238:241], v224 offset:60416
	ds_read_b128 v[242:245], v224 offset:65024
	ds_read_b128 v[246:249], v224 offset:51232
	s_nop 1
	v_max_f32_e32 v211, v83, v83
	v_max_f32_e32 v212, v82, v82
	v_max_f32_e32 v211, v212, v211
	v_max3_f32 v211, v211, v84, v85
	v_max3_f32 v211, v211, v86, v87
	v_max3_f32 v211, v211, v88, v89
	v_max3_f32 v211, v211, v90, v91
	v_max3_f32 v211, v211, v92, v93
	v_max3_f32 v211, v211, v94, v95
	v_max3_f32 v211, v211, v96, v97
	v_max3_f32 v211, v211, v66, v67
	v_max3_f32 v211, v211, v68, v69
	v_max3_f32 v211, v211, v70, v71
	v_max3_f32 v211, v211, v72, v73
	v_max3_f32 v211, v211, v74, v75
	v_max3_f32 v211, v211, v76, v77
	v_max3_f32 v211, v211, v78, v79
	v_max3_f32 v211, v211, v80, v81
	ds_bpermute_b32 v212, v207, v211
	s_waitcnt lgkmcnt(0)
	v_max_f32_e32 v212, v212, v212
	v_max_f32_e32 v211, v211, v212
	v_mul_f32_e32 v211, 0x3dd53b94, v211
	v_max_f32_e32 v212, v0, v0
	v_max_f32_e32 v211, v212, v211
	v_sub_f32_e32 v0, v0, v211
	v_exp_f32_e32 v0, v0
	s_nop 0
	v_cmp_neq_f32_e32 vcc, 1.0, v0
	s_cbranch_vccz .LBB0_549
; DI void attn_item(const Ctx& c, int item) {
;     ...
;     if (__builtin_amdgcn_ballot_w64(alpha != 1.0f) != 0ull) {
; #pragma unroll
;       for (int dt = 0; dt < 4; ++dt)
; #pragma unroll
;         for (int i = 0; i < 16; ++i) oacc[dt][i] *= alpha;
;     }
	v_pk_mul_f32 v[64:65], v[64:65], v[0:1] op_sel_hi:[1,0]
	v_pk_mul_f32 v[62:63], v[62:63], v[0:1] op_sel_hi:[1,0]
	v_pk_mul_f32 v[60:61], v[60:61], v[0:1] op_sel_hi:[1,0]
	v_pk_mul_f32 v[58:59], v[58:59], v[0:1] op_sel_hi:[1,0]
	v_pk_mul_f32 v[56:57], v[56:57], v[0:1] op_sel_hi:[1,0]
	v_pk_mul_f32 v[54:55], v[54:55], v[0:1] op_sel_hi:[1,0]
	v_pk_mul_f32 v[52:53], v[52:53], v[0:1] op_sel_hi:[1,0]
	v_pk_mul_f32 v[50:51], v[50:51], v[0:1] op_sel_hi:[1,0]
	v_pk_mul_f32 v[48:49], v[48:49], v[0:1] op_sel_hi:[1,0]
	v_pk_mul_f32 v[46:47], v[46:47], v[0:1] op_sel_hi:[1,0]
	v_pk_mul_f32 v[44:45], v[44:45], v[0:1] op_sel_hi:[1,0]
	v_pk_mul_f32 v[42:43], v[42:43], v[0:1] op_sel_hi:[1,0]
	v_pk_mul_f32 v[40:41], v[40:41], v[0:1] op_sel_hi:[1,0]
	v_pk_mul_f32 v[38:39], v[38:39], v[0:1] op_sel_hi:[1,0]
	v_pk_mul_f32 v[36:37], v[36:37], v[0:1] op_sel_hi:[1,0]
	v_pk_mul_f32 v[34:35], v[34:35], v[0:1] op_sel_hi:[1,0]
	v_pk_mul_f32 v[32:33], v[32:33], v[0:1] op_sel_hi:[1,0]
	v_pk_mul_f32 v[30:31], v[30:31], v[0:1] op_sel_hi:[1,0]
	v_pk_mul_f32 v[28:29], v[28:29], v[0:1] op_sel_hi:[1,0]
	v_pk_mul_f32 v[26:27], v[26:27], v[0:1] op_sel_hi:[1,0]
	v_pk_mul_f32 v[24:25], v[24:25], v[0:1] op_sel_hi:[1,0]
	v_pk_mul_f32 v[22:23], v[22:23], v[0:1] op_sel_hi:[1,0]
	v_pk_mul_f32 v[20:21], v[20:21], v[0:1] op_sel_hi:[1,0]
	v_pk_mul_f32 v[18:19], v[18:19], v[0:1] op_sel_hi:[1,0]
	v_pk_mul_f32 v[16:17], v[16:17], v[0:1] op_sel_hi:[1,0]
	v_pk_mul_f32 v[14:15], v[14:15], v[0:1] op_sel_hi:[1,0]
	v_pk_mul_f32 v[12:13], v[12:13], v[0:1] op_sel_hi:[1,0]
	v_pk_mul_f32 v[10:11], v[10:11], v[0:1] op_sel_hi:[1,0]
	v_pk_mul_f32 v[8:9], v[8:9], v[0:1] op_sel_hi:[1,0]
	v_pk_mul_f32 v[6:7], v[6:7], v[0:1] op_sel_hi:[1,0]
	v_pk_mul_f32 v[4:5], v[4:5], v[0:1] op_sel_hi:[1,0]
	v_pk_mul_f32 v[2:3], v[2:3], v[0:1] op_sel_hi:[1,0]
; #define MFMA32(a, b, c) __builtin_amdgcn_mfma_f32_32x32x16_bf16((a), (b), (c), 0, 0, 0)
; #define ATT_LOAD(KT)                                                                                    \
;   { _Pragma("unroll") for (int r = 0; r < 3; ++r) rk[r] = *(const u32x4*)(Kg + (size_t)((KT) * 64 + krow[r]) * 768 + kseg[r]); \
;     _Pragma("unroll") for (int r = 0; r < 2; ++r) rv[r] = *(const u32x4*)(Vg + (size_t)(vrow0 + 64 * r) * L + (KT) * 64 + vseg); }
; DI void attn_item(const Ctx& c, int item) {
;     ...
;     float ps = 0.f;
; #pragma unroll
;     for (int kg = 0; kg < 2; ++kg)
; #pragma unroll
;       for (int i = 0; i < 16; ++i) { s[kg][i] = __builtin_amdgcn_exp2f(s[kg][i] * sc - mn); ps += s[kg][i]; }
;     l_ = l_ * alpha + ps;
;     if (__builtin_amdgcn_ballot_w64(alpha != 1.0f) != 0ull) {
; #pragma unroll
;       for (int dt = 0; dt < 4; ++dt)
; #pragma unroll
;         for (int i = 0; i < 16; ++i) oacc[dt][i] *= alpha;
;     }
; #pragma unroll
;     for (int kg = 0; kg < 2; ++kg)
; #pragma unroll
;       for (int st = 0; st < 2; ++st) {
;         u32x4 pb;
;         pb[0] = pack2(s[kg][8 * st + 0], s[kg][8 * st + 1]); pb[1] = pack2(s[kg][8 * st + 2], s[kg][8 * st + 3]);
;         pb[2] = pack2(s[kg][8 * st + 4], s[kg][8 * st + 5]); pb[3] = pack2(s[kg][8 * st + 6], s[kg][8 * st + 7]);
;         const bf16x8 pbv = __builtin_bit_cast(bf16x8, pb);
; #pragma unroll
;         for (int dt = 0; dt < 4; ++dt) {
;           const bf16x8 av = *(const bf16x8*)(vs_ + (dt * 32 + r32) * 72 + kg * 32 + 16 * st + 8 * hh);
;           oacc[dt] = MFMA32(av, pbv, oacc[dt]);
;         }
;       }
;     if (kt + 1 < ntile) ATT_STORE((kt + 1) & 1)
;     if (kt + 2 < ntile) ATT_LOAD(kt + 2)
;     __syncthreads();
;   }
.LBB0_549:
	v_fma_f32 v82, v82, s7, -v211
	v_fma_f32 v83, v83, s7, -v211
	v_fma_f32 v84, v84, s7, -v211
	v_fma_f32 v85, v85, s7, -v211
	v_fma_f32 v86, v86, s7, -v211
	v_fma_f32 v87, v87, s7, -v211
	v_fma_f32 v88, v88, s7, -v211
	v_fma_f32 v89, v89, s7, -v211
	v_exp_f32_e32 v82, v82
	v_exp_f32_e32 v83, v83
	v_exp_f32_e32 v84, v84
	v_exp_f32_e32 v85, v85
	v_exp_f32_e32 v86, v86
	v_exp_f32_e32 v87, v87
	v_exp_f32_e32 v88, v88
	v_exp_f32_e32 v89, v89
	s_nop 0
	v_cvt_pk_bf16_f32 v212, v82, v83
	v_cvt_pk_bf16_f32 v213, v84, v85
	v_cvt_pk_bf16_f32 v214, v86, v87
	v_cvt_pk_bf16_f32 v215, v88, v89
	s_nop 0
	s_waitcnt lgkmcnt(4)
	v_mfma_f32_32x32x16_bf16 v[50:65], v[230:233], v[212:215], v[50:65]
	ds_read_b128 v[230:233], v224 offset:55840
	v_fma_f32 v90, v90, s7, -v211
	v_fma_f32 v91, v91, s7, -v211
	v_fma_f32 v92, v92, s7, -v211
	v_fma_f32 v93, v93, s7, -v211
	v_exp_f32_e32 v90, v90
	v_exp_f32_e32 v91, v91
	s_waitcnt lgkmcnt(4)
	v_mfma_f32_32x32x16_bf16 v[34:49], v[234:237], v[212:215], v[34:49]
	ds_read_b128 v[234:237], v224 offset:60448
	v_fma_f32 v94, v94, s7, -v211
	v_fma_f32 v95, v95, s7, -v211
	v_fma_f32 v96, v96, s7, -v211
	v_fma_f32 v97, v97, s7, -v211
	v_exp_f32_e32 v92, v92
	v_exp_f32_e32 v93, v93
	s_waitcnt lgkmcnt(4)
	v_mfma_f32_32x32x16_bf16 v[18:33], v[238:241], v[212:215], v[18:33]
	ds_read_b128 v[238:241], v224 offset:65056
	v_exp_f32_e32 v94, v94
	v_exp_f32_e32 v95, v95
	v_exp_f32_e32 v96, v96
	v_exp_f32_e32 v97, v97
	v_cvt_pk_bf16_f32 v250, v90, v91
	v_cvt_pk_bf16_f32 v251, v92, v93
	s_waitcnt lgkmcnt(4)
	v_mfma_f32_32x32x16_bf16 v[2:17], v[242:245], v[212:215], v[2:17]
	ds_read_b128 v[242:245], v224 offset:51264
	v_cvt_pk_bf16_f32 v252, v94, v95
	v_cvt_pk_bf16_f32 v253, v96, v97
	s_nop 0
	s_waitcnt lgkmcnt(4)
	v_mfma_f32_32x32x16_bf16 v[50:65], v[246:249], v[250:253], v[50:65]
	ds_read_b128 v[246:249], v224 offset:55872
	v_fma_f32 v66, v66, s7, -v211
	v_fma_f32 v67, v67, s7, -v211
	v_fma_f32 v68, v68, s7, -v211
	v_fma_f32 v69, v69, s7, -v211
	v_exp_f32_e32 v66, v66
	v_exp_f32_e32 v67, v67
	s_waitcnt lgkmcnt(4)
	v_mfma_f32_32x32x16_bf16 v[34:49], v[230:233], v[250:253], v[34:49]
	ds_read_b128 v[230:233], v224 offset:60480
	v_fma_f32 v70, v70, s7, -v211
	v_fma_f32 v71, v71, s7, -v211
	v_fma_f32 v72, v72, s7, -v211
	v_fma_f32 v73, v73, s7, -v211
	v_exp_f32_e32 v68, v68
	v_exp_f32_e32 v69, v69
	s_waitcnt lgkmcnt(4)
	v_mfma_f32_32x32x16_bf16 v[18:33], v[234:237], v[250:253], v[18:33]
	ds_read_b128 v[234:237], v224 offset:65088
	v_exp_f32_e32 v70, v70
	v_exp_f32_e32 v71, v71
	v_exp_f32_e32 v72, v72
	v_exp_f32_e32 v73, v73
	v_cvt_pk_bf16_f32 v212, v66, v67
	v_cvt_pk_bf16_f32 v213, v68, v69
	s_waitcnt lgkmcnt(4)
	v_mfma_f32_32x32x16_bf16 v[2:17], v[238:241], v[250:253], v[2:17]
	ds_read_b128 v[238:241], v224 offset:51296
	v_cvt_pk_bf16_f32 v214, v70, v71
	v_cvt_pk_bf16_f32 v215, v72, v73
	s_nop 0
	s_waitcnt lgkmcnt(4)
	v_mfma_f32_32x32x16_bf16 v[50:65], v[242:245], v[212:215], v[50:65]
	ds_read_b128 v[242:245], v224 offset:55904
	v_fma_f32 v74, v74, s7, -v211
	v_fma_f32 v75, v75, s7, -v211
	v_fma_f32 v76, v76, s7, -v211
	v_fma_f32 v77, v77, s7, -v211
	v_exp_f32_e32 v74, v74
	v_exp_f32_e32 v75, v75
	s_waitcnt lgkmcnt(4)
	v_mfma_f32_32x32x16_bf16 v[34:49], v[246:249], v[212:215], v[34:49]
	ds_read_b128 v[246:249], v224 offset:60512
	v_fma_f32 v78, v78, s7, -v211
	v_fma_f32 v79, v79, s7, -v211
	v_fma_f32 v80, v80, s7, -v211
	v_fma_f32 v81, v81, s7, -v211
	v_exp_f32_e32 v76, v76
	v_exp_f32_e32 v77, v77
	s_waitcnt lgkmcnt(4)
	v_mfma_f32_32x32x16_bf16 v[18:33], v[230:233], v[212:215], v[18:33]
	ds_read_b128 v[230:233], v224 offset:65120
	v_exp_f32_e32 v78, v78
	v_exp_f32_e32 v79, v79
	v_exp_f32_e32 v80, v80
	v_exp_f32_e32 v81, v81
	v_cvt_pk_bf16_f32 v250, v74, v75
	v_cvt_pk_bf16_f32 v251, v76, v77
	s_waitcnt lgkmcnt(4)
	v_mfma_f32_32x32x16_bf16 v[2:17], v[234:237], v[212:215], v[2:17]
	v_cvt_pk_bf16_f32 v252, v78, v79
	v_cvt_pk_bf16_f32 v253, v80, v81
	s_nop 0
	s_waitcnt lgkmcnt(3)
	v_mfma_f32_32x32x16_bf16 v[50:65], v[238:241], v[250:253], v[50:65]
	v_add_f32_e32 v82, v86, v82
	v_add_f32_e32 v83, v87, v83
	v_add_f32_e32 v84, v88, v84
	v_add_f32_e32 v85, v89, v85
	v_add_f32_e32 v82, v90, v82
	v_add_f32_e32 v83, v91, v83
	v_add_f32_e32 v84, v92, v84
	s_waitcnt lgkmcnt(2)
	v_mfma_f32_32x32x16_bf16 v[34:49], v[242:245], v[250:253], v[34:49]
	v_add_f32_e32 v85, v93, v85
	v_add_f32_e32 v82, v94, v82
	v_add_f32_e32 v83, v95, v83
	v_add_f32_e32 v84, v96, v84
	v_add_f32_e32 v85, v97, v85
	v_add_f32_e32 v82, v66, v82
	v_add_f32_e32 v83, v67, v83
	s_waitcnt lgkmcnt(1)
	v_mfma_f32_32x32x16_bf16 v[18:33], v[246:249], v[250:253], v[18:33]
	v_add_f32_e32 v84, v68, v84
	v_add_f32_e32 v85, v69, v85
	v_add_f32_e32 v82, v70, v82
	v_add_f32_e32 v83, v71, v83
	v_add_f32_e32 v84, v72, v84
	v_add_f32_e32 v85, v73, v85
	v_add_f32_e32 v82, v74, v82
	s_waitcnt lgkmcnt(0)
	v_mfma_f32_32x32x16_bf16 v[2:17], v[230:233], v[250:253], v[2:17]
	v_add_f32_e32 v83, v75, v83
	v_add_f32_e32 v84, v76, v84
	v_add_f32_e32 v85, v77, v85
	v_add_f32_e32 v82, v78, v82
	v_add_f32_e32 v83, v79, v83
	v_add_f32_e32 v84, v80, v84
	v_add_f32_e32 v85, v81, v85
	v_add_f32_e32 v82, v82, v83
	v_add_f32_e32 v84, v84, v85
	v_add_f32_e32 v66, v82, v84
	s_add_i32 s0, s4, 1
	s_cmp_ge_u32 s0, s8
.LBB0_553:
	s_add_i32 s82, s82, 64
	v_fmac_f32_e32 v66, v210, v0
	s_cmp_lg_u32 s8, s0
	s_waitcnt lgkmcnt(0)
	s_barrier
	s_cbranch_scc0 .LBB0_555
	v_mov_b32_e32 v210, v66
	s_mov_b32 s4, s0
	s_branch .LBB0_547

; DI int otid() { int t = (int)__builtin_amdgcn_workitem_id_x(); asm volatile("" : "+v"(t)); return t; }
; DI float ld_f(const bf16* p) { return bf2f(*p); }
; template <typename AT>
; DI void compute_rstd2(const AT* A, int lda, int Kn, float* rstd, int rows) {
;   const int tid = otid();
;   const int tpr = NTHR / rows;
;   const int row = tid / tpr, part = tid % tpr;
;   const AT* p = A + (size_t)row * lda + part * (Kn / tpr);
;   float s = 0.f;
;   for (int k = 0; k < Kn / tpr; ++k) { const float v = ld_f(p + k); s += v * v; }
;   s += __shfl_xor(s, 1); if (tpr == 4) s += __shfl_xor(s, 2);
;   __syncthreads();
;   if (part == 0) rstd[row] = rsqrtf(s / (float)Kn + EPS);
;   __syncthreads();
; }
; DI void post_mix_rows(const Ctx& c, int m0) {
;     ...
;   for (int it = 0; it < 16; ++it) {
;     const int t0 = m0 + (it & 1) * 64, c0 = (it >> 1) * 64, seq = t0 >> c.logL, n0 = t0 & (L - 1);
;     {
;       const int ch = tid >> 3, ts = (tid & 7) * 8;
;       *(uint4*)(tile + ch * 72 + ts) = *(const uint4*)(ZO + ((size_t)(seq * 512 + c0 + ch)) * L + n0 + ts);
;     }
;     __syncthreads();
;     {
;       const int tr = tid >> 3, cs = (tid & 7) * 8;
;       unsigned short v[8];
; #pragma unroll
;       for (int e = 0; e < 8; ++e) v[e] = tile[(cs + e) * 72 + tr];
;       uint4 o; o.x = v[0] | ((unsigned)v[1] << 16); o.y = v[2] | ((unsigned)v[3] << 16); o.z = v[4] | ((unsigned)v[5] << 16); o.w = v[6] | ((unsigned)v[7] << 16);
;       *(uint4*)(Oh + (size_t)(t0 + tr) * 512 + c0 + cs) = o;
;     }
;     __syncthreads();
;   }
.LBB0_795:
	v_ashrrev_i32_e32 v3, 31, v2
	v_lshlrev_b64 v[16:17], s87, v[2:3]
	v_lshl_add_u64 v[16:17], v[16:17], 1, v[4:5]
	global_load_dwordx4 v[16:19], v[16:17], off
	v_lshl_add_u64 v[20:21], v[12:13], 0, s[0:1]
	v_add_co_u32_e32 v20, vcc, s10, v20
	v_ashrrev_i32_e32 v7, 31, v6
	s_nop 0
	v_addc_co_u32_e32 v21, vcc, 0, v21, vcc
	v_add_u32_e32 v2, 64, v2
	s_waitcnt vmcnt(0)
	ds_write_b128 v14, v[16:19]
	s_waitcnt lgkmcnt(0)
	s_barrier
	ds_read_u16 v0, v15
	ds_read_u16 v3, v15 offset:144
	s_waitcnt lgkmcnt(0)
	v_lshl_or_b32 v16, v3, 16, v0
	ds_read_u16 v0, v15 offset:288
	ds_read_u16 v3, v15 offset:432
	s_waitcnt lgkmcnt(0)
	v_lshl_or_b32 v17, v3, 16, v0
	ds_read_u16 v0, v15 offset:576
	ds_read_u16 v3, v15 offset:720
	s_waitcnt lgkmcnt(0)
	v_lshl_or_b32 v18, v3, 16, v0
	ds_read_u16 v0, v15 offset:864
	ds_read_u16 v3, v15 offset:1008
	s_waitcnt lgkmcnt(0)
	v_lshl_or_b32 v19, v3, 16, v0
	global_store_dwordx4 v[20:21], v[16:19], off
	s_barrier
	s_nop 0
	v_lshlrev_b64 v[16:17], s87, v[6:7]
	v_lshl_add_u64 v[16:17], v[16:17], 1, v[8:9]
	global_load_dwordx4 v[16:19], v[16:17], off
	v_lshl_add_u64 v[20:21], v[10:11], 0, s[0:1]
	s_add_u32 s0, s0, 0x80
	v_add_co_u32_e32 v20, vcc, s10, v20
	s_addc_u32 s1, s1, 0
	s_nop 0
	v_addc_co_u32_e32 v21, vcc, 0, v21, vcc
	v_add_u32_e32 v6, 64, v6
	s_cmpk_lg_i32 s0, 0x400
	s_waitcnt vmcnt(0)
	ds_write_b128 v14, v[16:19]
	s_waitcnt lgkmcnt(0)
	s_barrier
	ds_read_u16 v0, v15
	ds_read_u16 v3, v15 offset:144
	s_waitcnt lgkmcnt(0)
	v_lshl_or_b32 v16, v3, 16, v0
	ds_read_u16 v0, v15 offset:288
	ds_read_u16 v3, v15 offset:432
	s_waitcnt lgkmcnt(0)
	v_lshl_or_b32 v17, v3, 16, v0
	ds_read_u16 v0, v15 offset:576
	ds_read_u16 v3, v15 offset:720
	s_waitcnt lgkmcnt(0)
	v_lshl_or_b32 v18, v3, 16, v0
	ds_read_u16 v0, v15 offset:864
	ds_read_u16 v3, v15 offset:1008
	s_waitcnt lgkmcnt(0)
	v_lshl_or_b32 v19, v3, 16, v0
	global_store_dwordx4 v[20:21], v[16:19], off
	s_barrier
	s_cbranch_scc1 .LBB0_795
	v_mov_b32_e32 v0, v186
	s_ashr_i32 s17, s16, 31
	v_ashrrev_i32_e32 v2, 31, v0
	v_lshrrev_b32_e32 v2, 30, v2
	v_add_u32_e32 v3, v0, v2
	v_ashrrev_i32_e32 v2, 2, v3
	v_and_b32_e32 v3, -4, v3
	v_sub_u32_e32 v0, v0, v3
	v_ashrrev_i32_e32 v3, 31, v2
	s_lshl_b64 s[0:1], s[16:17], 12
	v_lshlrev_b64 v[4:5], 12, v[2:3]
	v_lshlrev_b32_e32 v6, 8, v0
	v_ashrrev_i32_e32 v7, 31, v6
	v_lshl_add_u64 v[4:5], v[4:5], 0, s[0:1]
	v_readlane_b32 s0, v226, 19
	v_lshl_add_u64 v[4:5], v[6:7], 2, v[4:5]
	v_readlane_b32 s1, v226, 20
	v_mov_b32_e32 v3, 0
	s_nop 0
	v_lshl_add_u64 v[4:5], s[0:1], 0, v[4:5]
	s_mov_b64 s[0:1], 0
	v_mov_b32_e32 v246, v4
	v_mov_b32_e32 v247, v5
	s_mov_b32 s0, 0
	global_load_dwordx4 v[6:9], v[246:247], off
	global_load_dwordx4 v[10:13], v[246:247], off offset:16
	global_load_dwordx4 v[14:17], v[246:247], off offset:32
	global_load_dwordx4 v[18:21], v[246:247], off offset:48
	v_lshl_add_u64 v[246:247], v[246:247], 0, 64
.Lrstd_tail_loop:
	global_load_dwordx4 v[230:233], v[246:247], off
	global_load_dwordx4 v[234:237], v[246:247], off offset:16
	global_load_dwordx4 v[238:241], v[246:247], off offset:32
	global_load_dwordx4 v[242:245], v[246:247], off offset:48
	v_lshl_add_u64 v[246:247], v[246:247], 0, 64
	s_waitcnt vmcnt(4)
	v_fmac_f32_e32 v3, v6, v6
	v_fmac_f32_e32 v3, v7, v7
	v_fmac_f32_e32 v3, v8, v8
	v_fmac_f32_e32 v3, v9, v9
	v_fmac_f32_e32 v3, v10, v10
	v_fmac_f32_e32 v3, v11, v11
	v_fmac_f32_e32 v3, v12, v12
	v_fmac_f32_e32 v3, v13, v13
	v_fmac_f32_e32 v3, v14, v14
	v_fmac_f32_e32 v3, v15, v15
	v_fmac_f32_e32 v3, v16, v16
	v_fmac_f32_e32 v3, v17, v17
	v_fmac_f32_e32 v3, v18, v18
	v_fmac_f32_e32 v3, v19, v19
	v_fmac_f32_e32 v3, v20, v20
	v_fmac_f32_e32 v3, v21, v21
	s_add_u32 s0, s0, 128
	s_cmpk_eq_i32 s0, 0x400
	s_cbranch_scc1 .Lrstd_tail_last
	global_load_dwordx4 v[6:9], v[246:247], off
	global_load_dwordx4 v[10:13], v[246:247], off offset:16
	global_load_dwordx4 v[14:17], v[246:247], off offset:32
	global_load_dwordx4 v[18:21], v[246:247], off offset:48
	v_lshl_add_u64 v[246:247], v[246:247], 0, 64
	s_waitcnt vmcnt(4)
	v_fmac_f32_e32 v3, v230, v230
	v_fmac_f32_e32 v3, v231, v231
	v_fmac_f32_e32 v3, v232, v232
	v_fmac_f32_e32 v3, v233, v233
	v_fmac_f32_e32 v3, v234, v234
	v_fmac_f32_e32 v3, v235, v235
	v_fmac_f32_e32 v3, v236, v236
	v_fmac_f32_e32 v3, v237, v237
	v_fmac_f32_e32 v3, v238, v238
	v_fmac_f32_e32 v3, v239, v239
	v_fmac_f32_e32 v3, v240, v240
	v_fmac_f32_e32 v3, v241, v241
	v_fmac_f32_e32 v3, v242, v242
	v_fmac_f32_e32 v3, v243, v243
	v_fmac_f32_e32 v3, v244, v244
	v_fmac_f32_e32 v3, v245, v245
	s_branch .Lrstd_tail_loop
.Lrstd_tail_last:
	s_waitcnt vmcnt(0)
	v_fmac_f32_e32 v3, v230, v230
	v_fmac_f32_e32 v3, v231, v231
	v_fmac_f32_e32 v3, v232, v232
	v_fmac_f32_e32 v3, v233, v233
	v_fmac_f32_e32 v3, v234, v234
	v_fmac_f32_e32 v3, v235, v235
	v_fmac_f32_e32 v3, v236, v236
	v_fmac_f32_e32 v3, v237, v237
	v_fmac_f32_e32 v3, v238, v238
	v_fmac_f32_e32 v3, v239, v239
	v_fmac_f32_e32 v3, v240, v240
	v_fmac_f32_e32 v3, v241, v241
	v_fmac_f32_e32 v3, v242, v242
	v_fmac_f32_e32 v3, v243, v243
	v_fmac_f32_e32 v3, v244, v244
	v_fmac_f32_e32 v3, v245, v245
	v_and_b32_e32 v5, 64, v189
	v_xor_b32_e32 v4, 1, v189
	v_add_u32_e32 v122, 64, v5
	v_cmp_lt_i32_e32 vcc, v4, v122
	s_barrier
	s_nop 0
	v_cndmask_b32_e32 v4, v189, v4, vcc
	v_lshlrev_b32_e32 v164, 2, v4
	ds_bpermute_b32 v4, v164, v3
	s_waitcnt lgkmcnt(0)
	v_add_f32_e32 v3, v3, v4
	v_xor_b32_e32 v4, 2, v189
	v_cmp_lt_i32_e32 vcc, v4, v122
	s_nop 1
	v_cndmask_b32_e32 v4, v189, v4, vcc
	v_lshlrev_b32_e32 v163, 2, v4
	ds_bpermute_b32 v4, v163, v3
	v_cmp_eq_u32_e32 vcc, 0, v0
	s_and_saveexec_b64 s[0:1], vcc
	s_cbranch_execz .LBB0_800
	s_waitcnt lgkmcnt(0)
	v_add_f32_e32 v0, v3, v4
	v_fmamk_f32 v0, v0, 0x3a800000, v187
	s_mov_b32 s10, 0x800000
	v_mul_f32_e32 v3, 0x4b800000, v0
	v_cmp_gt_f32_e32 vcc, s10, v0
	v_lshl_add_u32 v2, v2, 2, v190
	v_add_u32_e32 v2, 0x24000, v2
	v_cndmask_b32_e32 v0, v0, v3, vcc
	v_rsq_f32_e32 v0, v0
	s_nop 0
	v_mul_f32_e32 v3, 0x45800000, v0
	v_cndmask_b32_e32 v0, v0, v3, vcc
	ds_write_b32 v2, v0
